# P1 K-loop: LDS-DMA loads in saddr form (no per-load 64-bit VALU add)
# speedup vs baseline: 1.0108x; 1.0015x over previous
.LBB0_130:
	s_ashr_i32 s13, s12, 31
	s_lshl_b64 s[14:15], s[12:13], 19
	v_readlane_b32 s16, v254, 39
	v_readlane_b32 s17, v254, 40
	s_add_u32 s14, s16, s14
	s_addc_u32 s15, s17, s15
	s_and_b64 s[16:17], s[0:1], exec
	s_cselect_b32 s13, s15, s19
	s_cselect_b32 s42, s14, s18
	s_ashr_i32 s11, s10, 31
	s_lshl_b64 s[16:17], s[10:11], 19
	s_add_u32 s16, s24, s16
	s_addc_u32 s17, s25, s17
	s_and_b64 s[22:23], s[0:1], exec
	s_cselect_b32 s11, s17, s21
	s_cselect_b32 s43, s16, s20
	s_add_u32 s18, s18, 0x40080
	s_addc_u32 s19, s19, 0
	s_add_u32 s44, s20, 0x100
	s_addc_u32 s45, s21, 0
	s_mov_b32 s46, -2
	ds_read_b128 v[152:155], v148
	ds_read_b128 v[156:159], v148 offset:1024
	ds_read_b128 v[160:163], v148 offset:2048
	ds_read_b128 v[164:167], v148 offset:3072
	ds_read_b128 v[168:171], v149
	ds_read_b128 v[172:175], v149 offset:1024
	ds_read_b128 v[176:179], v149 offset:2048
	ds_read_b128 v[180:183], v149 offset:3072
	s_add_u32 s20, s18, 0xfffc0080
	s_addc_u32 s21, s19, -1
	s_cmp_eq_u32 s46, 12
	s_cselect_b32 s23, s13, s21
	s_cselect_b32 s22, s42, s20
	s_cselect_b32 s21, s11, s45
	s_cselect_b32 s20, s43, s44
	s_add_i32 m0, s9, 0xc000
	ds_read_b128 v[184:187], v150
	ds_read_b128 v[188:191], v150 offset:1024
	ds_read_b128 v[192:195], v150 offset:2048
	ds_read_b128 v[196:199], v150 offset:3072
	ds_read_b128 v[200:203], v150 offset:4096
	ds_read_b128 v[204:207], v150 offset:5120
	ds_read_b128 v[208:211], v150 offset:6144
	ds_read_b128 v[212:215], v150 offset:7168
	global_load_lds_dwordx4 v136, s[18:19]
	s_add_i32 m0, s9, 0xe000
	s_nop 0
	global_load_lds_dwordx4 v138, s[18:19]
	s_waitcnt vmcnt(8)
	s_waitcnt lgkmcnt(0)
	s_barrier
	s_setprio 1
	s_waitcnt lgkmcnt(0)
	v_mfma_f32_16x16x32_bf16 v[124:127], v[152:155], v[184:187], 0
	v_mfma_f32_16x16x32_bf16 v[120:123], v[160:163], v[184:187], 0
	v_mfma_f32_16x16x32_bf16 v[116:119], v[152:155], v[192:195], 0
	v_mfma_f32_16x16x32_bf16 v[112:115], v[160:163], v[192:195], 0
	v_mfma_f32_16x16x32_bf16 v[100:103], v[152:155], v[200:203], 0
	v_mfma_f32_16x16x32_bf16 v[96:99], v[160:163], v[200:203], 0
	v_mfma_f32_16x16x32_bf16 v[84:87], v[152:155], v[208:211], 0
	v_mfma_f32_16x16x32_bf16 v[80:83], v[160:163], v[208:211], 0
	v_mfma_f32_16x16x32_bf16 v[124:127], v[156:159], v[188:191], v[124:127]
	v_mfma_f32_16x16x32_bf16 v[120:123], v[164:167], v[188:191], v[120:123]
	v_mfma_f32_16x16x32_bf16 v[116:119], v[156:159], v[196:199], v[116:119]
	v_mfma_f32_16x16x32_bf16 v[112:115], v[164:167], v[196:199], v[112:115]
	v_mfma_f32_16x16x32_bf16 v[100:103], v[156:159], v[204:207], v[100:103]
	v_mfma_f32_16x16x32_bf16 v[96:99], v[164:167], v[204:207], v[96:99]
	v_mfma_f32_16x16x32_bf16 v[84:87], v[156:159], v[212:215], v[84:87]
	v_mfma_f32_16x16x32_bf16 v[80:83], v[164:167], v[212:215], v[80:83]
	s_setprio 0
	s_setprio 1
	v_mfma_f32_16x16x32_bf16 v[108:111], v[168:171], v[184:187], 0
	v_mfma_f32_16x16x32_bf16 v[104:107], v[176:179], v[184:187], 0
	v_mfma_f32_16x16x32_bf16 v[92:95], v[168:171], v[192:195], 0
	v_mfma_f32_16x16x32_bf16 v[88:91], v[176:179], v[192:195], 0
	v_mfma_f32_16x16x32_bf16 v[76:79], v[168:171], v[200:203], 0
	v_mfma_f32_16x16x32_bf16 v[72:75], v[176:179], v[200:203], 0
	v_mfma_f32_16x16x32_bf16 v[68:71], v[168:171], v[208:211], 0
	v_mfma_f32_16x16x32_bf16 v[64:67], v[176:179], v[208:211], 0
	v_mfma_f32_16x16x32_bf16 v[108:111], v[172:175], v[188:191], v[108:111]
	v_mfma_f32_16x16x32_bf16 v[104:107], v[180:183], v[188:191], v[104:107]
	v_mfma_f32_16x16x32_bf16 v[92:95], v[172:175], v[196:199], v[92:95]
	v_mfma_f32_16x16x32_bf16 v[88:91], v[180:183], v[196:199], v[88:91]
	v_mfma_f32_16x16x32_bf16 v[76:79], v[172:175], v[204:207], v[76:79]
	v_mfma_f32_16x16x32_bf16 v[72:75], v[180:183], v[204:207], v[72:75]
	v_mfma_f32_16x16x32_bf16 v[68:71], v[172:175], v[212:215], v[68:71]
	v_mfma_f32_16x16x32_bf16 v[64:67], v[180:183], v[212:215], v[64:67]
	s_setprio 0
	s_barrier
	s_add_i32 s47, s38, s26
	s_mov_b32 m0, s47
	ds_read_b128 v[184:187], v150 offset:16384
	ds_read_b128 v[188:191], v150 offset:17408
	ds_read_b128 v[192:195], v150 offset:18432
	ds_read_b128 v[196:199], v150 offset:19456
	ds_read_b128 v[200:203], v150 offset:20480
	ds_read_b128 v[204:207], v150 offset:21504
	ds_read_b128 v[208:211], v150 offset:22528
	ds_read_b128 v[212:215], v150 offset:23552
	global_load_lds_dwordx4 v132, s[20:21]
	s_add_i32 m0, s47, 0x2000
	s_add_u32 s48, s20, 0x40000
	s_addc_u32 s49, s21, 0
	s_add_i32 s47, s39, s26
	global_load_lds_dwordx4 v128, s[20:21]
	s_mov_b32 m0, s47
	s_nop 0
	global_load_lds_dwordx4 v132, s[48:49]
	s_add_i32 m0, s47, 0x2000
	s_nop 0
	global_load_lds_dwordx4 v128, s[48:49]
	s_mov_b32 m0, s9
	s_nop 0
	global_load_lds_dwordx4 v134, s[22:23]
	s_mov_b32 m0, s29
	s_nop 0
	global_load_lds_dwordx4 v130, s[22:23]
	s_add_u32 s84, s20, s4
	s_addc_u32 s85, s21, s5
	s_add_u32 s86, s22, s4
	s_addc_u32 s87, s23, s5
	s_waitcnt vmcnt(8)
	s_waitcnt lgkmcnt(0)
	s_barrier
	s_setprio 1
	s_waitcnt lgkmcnt(0)
	v_mfma_f32_16x16x32_bf16 v[60:63], v[152:155], v[184:187], 0
	v_mfma_f32_16x16x32_bf16 v[56:59], v[160:163], v[184:187], 0
	v_mfma_f32_16x16x32_bf16 v[52:55], v[152:155], v[192:195], 0
	v_mfma_f32_16x16x32_bf16 v[48:51], v[160:163], v[192:195], 0
	v_mfma_f32_16x16x32_bf16 v[36:39], v[152:155], v[200:203], 0
	v_mfma_f32_16x16x32_bf16 v[32:35], v[160:163], v[200:203], 0
	v_mfma_f32_16x16x32_bf16 v[20:23], v[152:155], v[208:211], 0
	v_mfma_f32_16x16x32_bf16 v[16:19], v[160:163], v[208:211], 0
	v_mfma_f32_16x16x32_bf16 v[60:63], v[156:159], v[188:191], v[60:63]
	v_mfma_f32_16x16x32_bf16 v[56:59], v[164:167], v[188:191], v[56:59]
	v_mfma_f32_16x16x32_bf16 v[52:55], v[156:159], v[196:199], v[52:55]
	v_mfma_f32_16x16x32_bf16 v[48:51], v[164:167], v[196:199], v[48:51]
	v_mfma_f32_16x16x32_bf16 v[36:39], v[156:159], v[204:207], v[36:39]
	v_mfma_f32_16x16x32_bf16 v[32:35], v[164:167], v[204:207], v[32:35]
	v_mfma_f32_16x16x32_bf16 v[20:23], v[156:159], v[212:215], v[20:23]
	v_mfma_f32_16x16x32_bf16 v[16:19], v[164:167], v[212:215], v[16:19]
	s_setprio 0
	s_setprio 1
	v_mfma_f32_16x16x32_bf16 v[44:47], v[168:171], v[184:187], 0
	v_mfma_f32_16x16x32_bf16 v[40:43], v[176:179], v[184:187], 0
	v_mfma_f32_16x16x32_bf16 v[28:31], v[168:171], v[192:195], 0
	v_mfma_f32_16x16x32_bf16 v[24:27], v[176:179], v[192:195], 0
	v_mfma_f32_16x16x32_bf16 v[12:15], v[168:171], v[200:203], 0
	v_mfma_f32_16x16x32_bf16 v[8:11], v[176:179], v[200:203], 0
	v_mfma_f32_16x16x32_bf16 v[4:7], v[168:171], v[208:211], 0
	v_mfma_f32_16x16x32_bf16 v[0:3], v[176:179], v[208:211], 0
	v_mfma_f32_16x16x32_bf16 v[44:47], v[172:175], v[188:191], v[44:47]
	v_mfma_f32_16x16x32_bf16 v[40:43], v[180:183], v[188:191], v[40:43]
	v_mfma_f32_16x16x32_bf16 v[28:31], v[172:175], v[196:199], v[28:31]
	v_mfma_f32_16x16x32_bf16 v[24:27], v[180:183], v[196:199], v[24:27]
	v_mfma_f32_16x16x32_bf16 v[12:15], v[172:175], v[204:207], v[12:15]
	v_mfma_f32_16x16x32_bf16 v[8:11], v[180:183], v[204:207], v[8:11]
	v_mfma_f32_16x16x32_bf16 v[4:7], v[172:175], v[212:215], v[4:7]
	v_mfma_f32_16x16x32_bf16 v[0:3], v[180:183], v[212:215], v[0:3]
	s_setprio 0
	s_barrier
	s_add_i32 s47, 0, 0x18000
	v_add_u32_e32 v151, s47, v146
	s_add_i32 s48, 0, 0x1c000
	ds_read_b128 v[152:155], v151
	ds_read_b128 v[156:159], v151 offset:1024
	ds_read_b128 v[160:163], v151 offset:2048
	ds_read_b128 v[164:167], v151 offset:3072
	v_add_u32_e32 v151, s48, v146
	ds_read_b128 v[168:171], v151
	ds_read_b128 v[172:175], v151 offset:1024
	ds_read_b128 v[176:179], v151 offset:2048
	ds_read_b128 v[180:183], v151 offset:3072
	s_add_u32 s22, s22, 0x40000
	s_addc_u32 s23, s23, 0
	s_mov_b32 m0, s30
	ds_read_b128 v[184:187], v150 offset:32768
	ds_read_b128 v[188:191], v150 offset:33792
	ds_read_b128 v[192:195], v150 offset:34816
	ds_read_b128 v[196:199], v150 offset:35840
	ds_read_b128 v[200:203], v150 offset:36864
	ds_read_b128 v[204:207], v150 offset:37888
	ds_read_b128 v[208:211], v150 offset:38912
	ds_read_b128 v[212:215], v150 offset:39936
	global_load_lds_dwordx4 v134, s[22:23]
	s_mov_b32 m0, s31
	s_nop 0
	global_load_lds_dwordx4 v130, s[22:23]
	s_waitcnt vmcnt(8)
	s_waitcnt lgkmcnt(0)
	s_barrier
	s_setprio 1
	s_waitcnt lgkmcnt(0)
	v_mfma_f32_16x16x32_bf16 v[124:127], v[152:155], v[184:187], v[124:127]
	v_mfma_f32_16x16x32_bf16 v[120:123], v[160:163], v[184:187], v[120:123]
	v_mfma_f32_16x16x32_bf16 v[116:119], v[152:155], v[192:195], v[116:119]
	v_mfma_f32_16x16x32_bf16 v[112:115], v[160:163], v[192:195], v[112:115]
	v_mfma_f32_16x16x32_bf16 v[100:103], v[152:155], v[200:203], v[100:103]
	v_mfma_f32_16x16x32_bf16 v[96:99], v[160:163], v[200:203], v[96:99]
	v_mfma_f32_16x16x32_bf16 v[84:87], v[152:155], v[208:211], v[84:87]
	v_mfma_f32_16x16x32_bf16 v[80:83], v[160:163], v[208:211], v[80:83]
	v_mfma_f32_16x16x32_bf16 v[124:127], v[156:159], v[188:191], v[124:127]
	v_mfma_f32_16x16x32_bf16 v[120:123], v[164:167], v[188:191], v[120:123]
	v_mfma_f32_16x16x32_bf16 v[116:119], v[156:159], v[196:199], v[116:119]
	v_mfma_f32_16x16x32_bf16 v[112:115], v[164:167], v[196:199], v[112:115]
	v_mfma_f32_16x16x32_bf16 v[100:103], v[156:159], v[204:207], v[100:103]
	v_mfma_f32_16x16x32_bf16 v[96:99], v[164:167], v[204:207], v[96:99]
	v_mfma_f32_16x16x32_bf16 v[84:87], v[156:159], v[212:215], v[84:87]
	v_mfma_f32_16x16x32_bf16 v[80:83], v[164:167], v[212:215], v[80:83]
	s_setprio 0
	s_setprio 1
	v_mfma_f32_16x16x32_bf16 v[108:111], v[168:171], v[184:187], v[108:111]
	v_mfma_f32_16x16x32_bf16 v[104:107], v[176:179], v[184:187], v[104:107]
	v_mfma_f32_16x16x32_bf16 v[92:95], v[168:171], v[192:195], v[92:95]
	v_mfma_f32_16x16x32_bf16 v[88:91], v[176:179], v[192:195], v[88:91]
	v_mfma_f32_16x16x32_bf16 v[76:79], v[168:171], v[200:203], v[76:79]
	v_mfma_f32_16x16x32_bf16 v[72:75], v[176:179], v[200:203], v[72:75]
	v_mfma_f32_16x16x32_bf16 v[68:71], v[168:171], v[208:211], v[68:71]
	v_mfma_f32_16x16x32_bf16 v[64:67], v[176:179], v[208:211], v[64:67]
	v_mfma_f32_16x16x32_bf16 v[108:111], v[172:175], v[188:191], v[108:111]
	v_mfma_f32_16x16x32_bf16 v[104:107], v[180:183], v[188:191], v[104:107]
	v_mfma_f32_16x16x32_bf16 v[92:95], v[172:175], v[196:199], v[92:95]
	v_mfma_f32_16x16x32_bf16 v[88:91], v[180:183], v[196:199], v[88:91]
	v_mfma_f32_16x16x32_bf16 v[76:79], v[172:175], v[204:207], v[76:79]
	v_mfma_f32_16x16x32_bf16 v[72:75], v[180:183], v[204:207], v[72:75]
	v_mfma_f32_16x16x32_bf16 v[68:71], v[172:175], v[212:215], v[68:71]
	v_mfma_f32_16x16x32_bf16 v[64:67], v[180:183], v[212:215], v[64:67]
	s_setprio 0
	s_barrier
	s_add_i32 s22, s47, s26
	s_mov_b32 m0, s22
	ds_read_b128 v[184:187], v150 offset:49152
	ds_read_b128 v[188:191], v150 offset:50176
	ds_read_b128 v[192:195], v150 offset:51200
	ds_read_b128 v[196:199], v150 offset:52224
	ds_read_b128 v[200:203], v150 offset:53248
	ds_read_b128 v[204:207], v150 offset:54272
	ds_read_b128 v[208:211], v150 offset:55296
	ds_read_b128 v[212:215], v150 offset:56320
	global_load_lds_dwordx4 v132, s[84:85]
	s_add_i32 m0, s22, 0x2000
	s_add_u32 s20, s20, 0x40080
	s_addc_u32 s21, s21, 0
	s_add_i32 s22, s48, s26
	global_load_lds_dwordx4 v128, s[84:85]
	s_mov_b32 m0, s22
	s_nop 0
	global_load_lds_dwordx4 v132, s[20:21]
	s_add_i32 m0, s22, 0x2000
	s_nop 0
	global_load_lds_dwordx4 v128, s[20:21]
	s_mov_b32 m0, s34
	s_nop 0
	global_load_lds_dwordx4 v134, s[86:87]
	s_mov_b32 m0, s35
	s_nop 0
	global_load_lds_dwordx4 v130, s[86:87]
	s_waitcnt vmcnt(8)
	s_waitcnt lgkmcnt(0)
	s_barrier
	s_setprio 1
	s_waitcnt lgkmcnt(0)
	v_mfma_f32_16x16x32_bf16 v[60:63], v[152:155], v[184:187], v[60:63]
	v_mfma_f32_16x16x32_bf16 v[56:59], v[160:163], v[184:187], v[56:59]
	v_mfma_f32_16x16x32_bf16 v[52:55], v[152:155], v[192:195], v[52:55]
	v_mfma_f32_16x16x32_bf16 v[48:51], v[160:163], v[192:195], v[48:51]
	v_mfma_f32_16x16x32_bf16 v[36:39], v[152:155], v[200:203], v[36:39]
	v_mfma_f32_16x16x32_bf16 v[32:35], v[160:163], v[200:203], v[32:35]
	v_mfma_f32_16x16x32_bf16 v[20:23], v[152:155], v[208:211], v[20:23]
	v_mfma_f32_16x16x32_bf16 v[16:19], v[160:163], v[208:211], v[16:19]
	v_mfma_f32_16x16x32_bf16 v[60:63], v[156:159], v[188:191], v[60:63]
	v_mfma_f32_16x16x32_bf16 v[56:59], v[164:167], v[188:191], v[56:59]
	v_mfma_f32_16x16x32_bf16 v[52:55], v[156:159], v[196:199], v[52:55]
	v_mfma_f32_16x16x32_bf16 v[48:51], v[164:167], v[196:199], v[48:51]
	v_mfma_f32_16x16x32_bf16 v[36:39], v[156:159], v[204:207], v[36:39]
	v_mfma_f32_16x16x32_bf16 v[32:35], v[164:167], v[204:207], v[32:35]
	v_mfma_f32_16x16x32_bf16 v[20:23], v[156:159], v[212:215], v[20:23]
	v_mfma_f32_16x16x32_bf16 v[16:19], v[164:167], v[212:215], v[16:19]
	s_setprio 0
	s_setprio 1
	v_mfma_f32_16x16x32_bf16 v[44:47], v[168:171], v[184:187], v[44:47]
	v_mfma_f32_16x16x32_bf16 v[40:43], v[176:179], v[184:187], v[40:43]
	v_mfma_f32_16x16x32_bf16 v[28:31], v[168:171], v[192:195], v[28:31]
	v_mfma_f32_16x16x32_bf16 v[24:27], v[176:179], v[192:195], v[24:27]
	v_mfma_f32_16x16x32_bf16 v[12:15], v[168:171], v[200:203], v[12:15]
	v_mfma_f32_16x16x32_bf16 v[8:11], v[176:179], v[200:203], v[8:11]
	v_mfma_f32_16x16x32_bf16 v[4:7], v[168:171], v[208:211], v[4:7]
	v_mfma_f32_16x16x32_bf16 v[0:3], v[176:179], v[208:211], v[0:3]
	v_mfma_f32_16x16x32_bf16 v[44:47], v[172:175], v[188:191], v[44:47]
	v_mfma_f32_16x16x32_bf16 v[40:43], v[180:183], v[188:191], v[40:43]
	v_mfma_f32_16x16x32_bf16 v[28:31], v[172:175], v[196:199], v[28:31]
	v_mfma_f32_16x16x32_bf16 v[24:27], v[180:183], v[196:199], v[24:27]
	v_mfma_f32_16x16x32_bf16 v[12:15], v[172:175], v[204:207], v[12:15]
	v_mfma_f32_16x16x32_bf16 v[8:11], v[180:183], v[204:207], v[8:11]
	v_mfma_f32_16x16x32_bf16 v[4:7], v[172:175], v[212:215], v[4:7]
	v_mfma_f32_16x16x32_bf16 v[0:3], v[180:183], v[212:215], v[0:3]
	s_setprio 0
	s_barrier
	s_add_i32 s46, s46, 2
	s_add_u32 s18, s18, 0x100
	s_addc_u32 s19, s19, 0
	s_add_u32 s44, s44, 0x100
	s_addc_u32 s45, s45, 0
.LBB0_131:
	ds_read_b128 v[152:155], v148
	ds_read_b128 v[156:159], v148 offset:1024
	ds_read_b128 v[160:163], v148 offset:2048
	ds_read_b128 v[164:167], v148 offset:3072
	ds_read_b128 v[168:171], v149
	ds_read_b128 v[172:175], v149 offset:1024
	ds_read_b128 v[176:179], v149 offset:2048
	ds_read_b128 v[180:183], v149 offset:3072
	s_add_u32 s20, s18, 0xfffc0080
	s_addc_u32 s21, s19, -1
	s_cmp_eq_u32 s46, 12
	s_cselect_b32 s23, s13, s21
	s_cselect_b32 s22, s42, s20
	s_cselect_b32 s21, s11, s45
	s_cselect_b32 s20, s43, s44
	s_add_i32 m0, s9, 0xc000
	ds_read_b128 v[184:187], v150
	ds_read_b128 v[188:191], v150 offset:1024
	ds_read_b128 v[192:195], v150 offset:2048
	ds_read_b128 v[196:199], v150 offset:3072
	ds_read_b128 v[200:203], v150 offset:4096
	ds_read_b128 v[204:207], v150 offset:5120
	ds_read_b128 v[208:211], v150 offset:6144
	ds_read_b128 v[212:215], v150 offset:7168
	global_load_lds_dwordx4 v136, s[18:19]
	s_add_i32 m0, s9, 0xe000
	s_nop 0
	global_load_lds_dwordx4 v138, s[18:19]
	s_waitcnt vmcnt(8)
	s_waitcnt lgkmcnt(0)
	s_barrier
	s_setprio 1
	s_waitcnt lgkmcnt(0)
	v_mfma_f32_16x16x32_bf16 v[124:127], v[152:155], v[184:187], v[124:127]
	v_mfma_f32_16x16x32_bf16 v[120:123], v[160:163], v[184:187], v[120:123]
	v_mfma_f32_16x16x32_bf16 v[116:119], v[152:155], v[192:195], v[116:119]
	v_mfma_f32_16x16x32_bf16 v[112:115], v[160:163], v[192:195], v[112:115]
	v_mfma_f32_16x16x32_bf16 v[100:103], v[152:155], v[200:203], v[100:103]
	v_mfma_f32_16x16x32_bf16 v[96:99], v[160:163], v[200:203], v[96:99]
	v_mfma_f32_16x16x32_bf16 v[84:87], v[152:155], v[208:211], v[84:87]
	v_mfma_f32_16x16x32_bf16 v[80:83], v[160:163], v[208:211], v[80:83]
	v_mfma_f32_16x16x32_bf16 v[124:127], v[156:159], v[188:191], v[124:127]
	v_mfma_f32_16x16x32_bf16 v[120:123], v[164:167], v[188:191], v[120:123]
	v_mfma_f32_16x16x32_bf16 v[116:119], v[156:159], v[196:199], v[116:119]
	v_mfma_f32_16x16x32_bf16 v[112:115], v[164:167], v[196:199], v[112:115]
	v_mfma_f32_16x16x32_bf16 v[100:103], v[156:159], v[204:207], v[100:103]
	v_mfma_f32_16x16x32_bf16 v[96:99], v[164:167], v[204:207], v[96:99]
	v_mfma_f32_16x16x32_bf16 v[84:87], v[156:159], v[212:215], v[84:87]
	v_mfma_f32_16x16x32_bf16 v[80:83], v[164:167], v[212:215], v[80:83]
	s_setprio 0
	s_setprio 1
	v_mfma_f32_16x16x32_bf16 v[108:111], v[168:171], v[184:187], v[108:111]
	v_mfma_f32_16x16x32_bf16 v[104:107], v[176:179], v[184:187], v[104:107]
	v_mfma_f32_16x16x32_bf16 v[92:95], v[168:171], v[192:195], v[92:95]
	v_mfma_f32_16x16x32_bf16 v[88:91], v[176:179], v[192:195], v[88:91]
	v_mfma_f32_16x16x32_bf16 v[76:79], v[168:171], v[200:203], v[76:79]
	v_mfma_f32_16x16x32_bf16 v[72:75], v[176:179], v[200:203], v[72:75]
	v_mfma_f32_16x16x32_bf16 v[68:71], v[168:171], v[208:211], v[68:71]
	v_mfma_f32_16x16x32_bf16 v[64:67], v[176:179], v[208:211], v[64:67]
	v_mfma_f32_16x16x32_bf16 v[108:111], v[172:175], v[188:191], v[108:111]
	v_mfma_f32_16x16x32_bf16 v[104:107], v[180:183], v[188:191], v[104:107]
	v_mfma_f32_16x16x32_bf16 v[92:95], v[172:175], v[196:199], v[92:95]
	v_mfma_f32_16x16x32_bf16 v[88:91], v[180:183], v[196:199], v[88:91]
	v_mfma_f32_16x16x32_bf16 v[76:79], v[172:175], v[204:207], v[76:79]
	v_mfma_f32_16x16x32_bf16 v[72:75], v[180:183], v[204:207], v[72:75]
	v_mfma_f32_16x16x32_bf16 v[68:71], v[172:175], v[212:215], v[68:71]
	v_mfma_f32_16x16x32_bf16 v[64:67], v[180:183], v[212:215], v[64:67]
	s_setprio 0
	s_barrier
	s_add_i32 s47, s38, s26
	s_mov_b32 m0, s47
	ds_read_b128 v[184:187], v150 offset:16384
	ds_read_b128 v[188:191], v150 offset:17408
	ds_read_b128 v[192:195], v150 offset:18432
	ds_read_b128 v[196:199], v150 offset:19456
	ds_read_b128 v[200:203], v150 offset:20480
	ds_read_b128 v[204:207], v150 offset:21504
	ds_read_b128 v[208:211], v150 offset:22528
	ds_read_b128 v[212:215], v150 offset:23552
	global_load_lds_dwordx4 v132, s[20:21]
	s_add_i32 m0, s47, 0x2000
	s_add_u32 s48, s20, 0x40000
	s_addc_u32 s49, s21, 0
	s_add_i32 s47, s39, s26
	global_load_lds_dwordx4 v128, s[20:21]
	s_mov_b32 m0, s47
	s_nop 0
	global_load_lds_dwordx4 v132, s[48:49]
	s_add_i32 m0, s47, 0x2000
	s_nop 0
	global_load_lds_dwordx4 v128, s[48:49]
	s_mov_b32 m0, s9
	s_nop 0
	global_load_lds_dwordx4 v134, s[22:23]
	s_mov_b32 m0, s29
	s_nop 0
	global_load_lds_dwordx4 v130, s[22:23]
	s_add_u32 s84, s20, s4
	s_addc_u32 s85, s21, s5
	s_add_u32 s86, s22, s4
	s_addc_u32 s87, s23, s5
	s_waitcnt vmcnt(8)
	s_waitcnt lgkmcnt(0)
	s_barrier
	s_setprio 1
	s_waitcnt lgkmcnt(0)
	v_mfma_f32_16x16x32_bf16 v[60:63], v[152:155], v[184:187], v[60:63]
	v_mfma_f32_16x16x32_bf16 v[56:59], v[160:163], v[184:187], v[56:59]
	v_mfma_f32_16x16x32_bf16 v[52:55], v[152:155], v[192:195], v[52:55]
	v_mfma_f32_16x16x32_bf16 v[48:51], v[160:163], v[192:195], v[48:51]
	v_mfma_f32_16x16x32_bf16 v[36:39], v[152:155], v[200:203], v[36:39]
	v_mfma_f32_16x16x32_bf16 v[32:35], v[160:163], v[200:203], v[32:35]
	v_mfma_f32_16x16x32_bf16 v[20:23], v[152:155], v[208:211], v[20:23]
	v_mfma_f32_16x16x32_bf16 v[16:19], v[160:163], v[208:211], v[16:19]
	v_mfma_f32_16x16x32_bf16 v[60:63], v[156:159], v[188:191], v[60:63]
	v_mfma_f32_16x16x32_bf16 v[56:59], v[164:167], v[188:191], v[56:59]
	v_mfma_f32_16x16x32_bf16 v[52:55], v[156:159], v[196:199], v[52:55]
	v_mfma_f32_16x16x32_bf16 v[48:51], v[164:167], v[196:199], v[48:51]
	v_mfma_f32_16x16x32_bf16 v[36:39], v[156:159], v[204:207], v[36:39]
	v_mfma_f32_16x16x32_bf16 v[32:35], v[164:167], v[204:207], v[32:35]
	v_mfma_f32_16x16x32_bf16 v[20:23], v[156:159], v[212:215], v[20:23]
	v_mfma_f32_16x16x32_bf16 v[16:19], v[164:167], v[212:215], v[16:19]
	s_setprio 0
	s_setprio 1
	v_mfma_f32_16x16x32_bf16 v[44:47], v[168:171], v[184:187], v[44:47]
	v_mfma_f32_16x16x32_bf16 v[40:43], v[176:179], v[184:187], v[40:43]
	v_mfma_f32_16x16x32_bf16 v[28:31], v[168:171], v[192:195], v[28:31]
	v_mfma_f32_16x16x32_bf16 v[24:27], v[176:179], v[192:195], v[24:27]
	v_mfma_f32_16x16x32_bf16 v[12:15], v[168:171], v[200:203], v[12:15]
	v_mfma_f32_16x16x32_bf16 v[8:11], v[176:179], v[200:203], v[8:11]
	v_mfma_f32_16x16x32_bf16 v[4:7], v[168:171], v[208:211], v[4:7]
	v_mfma_f32_16x16x32_bf16 v[0:3], v[176:179], v[208:211], v[0:3]
	v_mfma_f32_16x16x32_bf16 v[44:47], v[172:175], v[188:191], v[44:47]
	v_mfma_f32_16x16x32_bf16 v[40:43], v[180:183], v[188:191], v[40:43]
	v_mfma_f32_16x16x32_bf16 v[28:31], v[172:175], v[196:199], v[28:31]
	v_mfma_f32_16x16x32_bf16 v[24:27], v[180:183], v[196:199], v[24:27]
	v_mfma_f32_16x16x32_bf16 v[12:15], v[172:175], v[204:207], v[12:15]
	v_mfma_f32_16x16x32_bf16 v[8:11], v[180:183], v[204:207], v[8:11]
	v_mfma_f32_16x16x32_bf16 v[4:7], v[172:175], v[212:215], v[4:7]
	v_mfma_f32_16x16x32_bf16 v[0:3], v[180:183], v[212:215], v[0:3]
	s_setprio 0
	s_barrier
	s_add_i32 s47, 0, 0x18000
	v_add_u32_e32 v151, s47, v146
	s_add_i32 s48, 0, 0x1c000
	ds_read_b128 v[152:155], v151
	ds_read_b128 v[156:159], v151 offset:1024
	ds_read_b128 v[160:163], v151 offset:2048
	ds_read_b128 v[164:167], v151 offset:3072
	v_add_u32_e32 v151, s48, v146
	ds_read_b128 v[168:171], v151
	ds_read_b128 v[172:175], v151 offset:1024
	ds_read_b128 v[176:179], v151 offset:2048
	ds_read_b128 v[180:183], v151 offset:3072
	s_add_u32 s22, s22, 0x40000
	s_addc_u32 s23, s23, 0
	s_mov_b32 m0, s30
	ds_read_b128 v[184:187], v150 offset:32768
	ds_read_b128 v[188:191], v150 offset:33792
	ds_read_b128 v[192:195], v150 offset:34816
	ds_read_b128 v[196:199], v150 offset:35840
	ds_read_b128 v[200:203], v150 offset:36864
	ds_read_b128 v[204:207], v150 offset:37888
	ds_read_b128 v[208:211], v150 offset:38912
	ds_read_b128 v[212:215], v150 offset:39936
	global_load_lds_dwordx4 v134, s[22:23]
	s_mov_b32 m0, s31
	s_nop 0
	global_load_lds_dwordx4 v130, s[22:23]
	s_waitcnt vmcnt(8)
	s_waitcnt lgkmcnt(0)
	s_barrier
	s_setprio 1
	s_waitcnt lgkmcnt(0)
	v_mfma_f32_16x16x32_bf16 v[124:127], v[152:155], v[184:187], v[124:127]
	v_mfma_f32_16x16x32_bf16 v[120:123], v[160:163], v[184:187], v[120:123]
	v_mfma_f32_16x16x32_bf16 v[116:119], v[152:155], v[192:195], v[116:119]
	v_mfma_f32_16x16x32_bf16 v[112:115], v[160:163], v[192:195], v[112:115]
	v_mfma_f32_16x16x32_bf16 v[100:103], v[152:155], v[200:203], v[100:103]
	v_mfma_f32_16x16x32_bf16 v[96:99], v[160:163], v[200:203], v[96:99]
	v_mfma_f32_16x16x32_bf16 v[84:87], v[152:155], v[208:211], v[84:87]
	v_mfma_f32_16x16x32_bf16 v[80:83], v[160:163], v[208:211], v[80:83]
	v_mfma_f32_16x16x32_bf16 v[124:127], v[156:159], v[188:191], v[124:127]
	v_mfma_f32_16x16x32_bf16 v[120:123], v[164:167], v[188:191], v[120:123]
	v_mfma_f32_16x16x32_bf16 v[116:119], v[156:159], v[196:199], v[116:119]
	v_mfma_f32_16x16x32_bf16 v[112:115], v[164:167], v[196:199], v[112:115]
	v_mfma_f32_16x16x32_bf16 v[100:103], v[156:159], v[204:207], v[100:103]
	v_mfma_f32_16x16x32_bf16 v[96:99], v[164:167], v[204:207], v[96:99]
	v_mfma_f32_16x16x32_bf16 v[84:87], v[156:159], v[212:215], v[84:87]
	v_mfma_f32_16x16x32_bf16 v[80:83], v[164:167], v[212:215], v[80:83]
	s_setprio 0
	s_setprio 1
	v_mfma_f32_16x16x32_bf16 v[108:111], v[168:171], v[184:187], v[108:111]
	v_mfma_f32_16x16x32_bf16 v[104:107], v[176:179], v[184:187], v[104:107]
	v_mfma_f32_16x16x32_bf16 v[92:95], v[168:171], v[192:195], v[92:95]
	v_mfma_f32_16x16x32_bf16 v[88:91], v[176:179], v[192:195], v[88:91]
	v_mfma_f32_16x16x32_bf16 v[76:79], v[168:171], v[200:203], v[76:79]
	v_mfma_f32_16x16x32_bf16 v[72:75], v[176:179], v[200:203], v[72:75]
	v_mfma_f32_16x16x32_bf16 v[68:71], v[168:171], v[208:211], v[68:71]
	v_mfma_f32_16x16x32_bf16 v[64:67], v[176:179], v[208:211], v[64:67]
	v_mfma_f32_16x16x32_bf16 v[108:111], v[172:175], v[188:191], v[108:111]
	v_mfma_f32_16x16x32_bf16 v[104:107], v[180:183], v[188:191], v[104:107]
	v_mfma_f32_16x16x32_bf16 v[92:95], v[172:175], v[196:199], v[92:95]
	v_mfma_f32_16x16x32_bf16 v[88:91], v[180:183], v[196:199], v[88:91]
	v_mfma_f32_16x16x32_bf16 v[76:79], v[172:175], v[204:207], v[76:79]
	v_mfma_f32_16x16x32_bf16 v[72:75], v[180:183], v[204:207], v[72:75]
	v_mfma_f32_16x16x32_bf16 v[68:71], v[172:175], v[212:215], v[68:71]
	v_mfma_f32_16x16x32_bf16 v[64:67], v[180:183], v[212:215], v[64:67]
	s_setprio 0
	s_barrier
	s_add_i32 s22, s47, s26
	s_mov_b32 m0, s22
	ds_read_b128 v[184:187], v150 offset:49152
	ds_read_b128 v[188:191], v150 offset:50176
	ds_read_b128 v[192:195], v150 offset:51200
	ds_read_b128 v[196:199], v150 offset:52224
	ds_read_b128 v[200:203], v150 offset:53248
	ds_read_b128 v[204:207], v150 offset:54272
	ds_read_b128 v[208:211], v150 offset:55296
	ds_read_b128 v[212:215], v150 offset:56320
	global_load_lds_dwordx4 v132, s[84:85]
	s_add_i32 m0, s22, 0x2000
	s_add_u32 s20, s20, 0x40080
	s_addc_u32 s21, s21, 0
	s_add_i32 s22, s48, s26
	global_load_lds_dwordx4 v128, s[84:85]
	s_mov_b32 m0, s22
	s_nop 0
	global_load_lds_dwordx4 v132, s[20:21]
	s_add_i32 m0, s22, 0x2000
	s_nop 0
	global_load_lds_dwordx4 v128, s[20:21]
	s_mov_b32 m0, s34
	s_nop 0
	global_load_lds_dwordx4 v134, s[86:87]
	s_mov_b32 m0, s35
	s_nop 0
	global_load_lds_dwordx4 v130, s[86:87]
	s_waitcnt vmcnt(8)
	s_waitcnt lgkmcnt(0)
	s_barrier
	s_setprio 1
	s_waitcnt lgkmcnt(0)
	v_mfma_f32_16x16x32_bf16 v[60:63], v[152:155], v[184:187], v[60:63]
	v_mfma_f32_16x16x32_bf16 v[56:59], v[160:163], v[184:187], v[56:59]
	v_mfma_f32_16x16x32_bf16 v[52:55], v[152:155], v[192:195], v[52:55]
	v_mfma_f32_16x16x32_bf16 v[48:51], v[160:163], v[192:195], v[48:51]
	v_mfma_f32_16x16x32_bf16 v[36:39], v[152:155], v[200:203], v[36:39]
	v_mfma_f32_16x16x32_bf16 v[32:35], v[160:163], v[200:203], v[32:35]
	v_mfma_f32_16x16x32_bf16 v[20:23], v[152:155], v[208:211], v[20:23]
	v_mfma_f32_16x16x32_bf16 v[16:19], v[160:163], v[208:211], v[16:19]
	v_mfma_f32_16x16x32_bf16 v[60:63], v[156:159], v[188:191], v[60:63]
	v_mfma_f32_16x16x32_bf16 v[56:59], v[164:167], v[188:191], v[56:59]
	v_mfma_f32_16x16x32_bf16 v[52:55], v[156:159], v[196:199], v[52:55]
	v_mfma_f32_16x16x32_bf16 v[48:51], v[164:167], v[196:199], v[48:51]
	v_mfma_f32_16x16x32_bf16 v[36:39], v[156:159], v[204:207], v[36:39]
	v_mfma_f32_16x16x32_bf16 v[32:35], v[164:167], v[204:207], v[32:35]
	v_mfma_f32_16x16x32_bf16 v[20:23], v[156:159], v[212:215], v[20:23]
	v_mfma_f32_16x16x32_bf16 v[16:19], v[164:167], v[212:215], v[16:19]
	s_setprio 0
	s_setprio 1
	v_mfma_f32_16x16x32_bf16 v[44:47], v[168:171], v[184:187], v[44:47]
	v_mfma_f32_16x16x32_bf16 v[40:43], v[176:179], v[184:187], v[40:43]
	v_mfma_f32_16x16x32_bf16 v[28:31], v[168:171], v[192:195], v[28:31]
	v_mfma_f32_16x16x32_bf16 v[24:27], v[176:179], v[192:195], v[24:27]
	v_mfma_f32_16x16x32_bf16 v[12:15], v[168:171], v[200:203], v[12:15]
	v_mfma_f32_16x16x32_bf16 v[8:11], v[176:179], v[200:203], v[8:11]
	v_mfma_f32_16x16x32_bf16 v[4:7], v[168:171], v[208:211], v[4:7]
	v_mfma_f32_16x16x32_bf16 v[0:3], v[176:179], v[208:211], v[0:3]
	v_mfma_f32_16x16x32_bf16 v[44:47], v[172:175], v[188:191], v[44:47]
	v_mfma_f32_16x16x32_bf16 v[40:43], v[180:183], v[188:191], v[40:43]
	v_mfma_f32_16x16x32_bf16 v[28:31], v[172:175], v[196:199], v[28:31]
	v_mfma_f32_16x16x32_bf16 v[24:27], v[180:183], v[196:199], v[24:27]
	v_mfma_f32_16x16x32_bf16 v[12:15], v[172:175], v[204:207], v[12:15]
	v_mfma_f32_16x16x32_bf16 v[8:11], v[180:183], v[204:207], v[8:11]
	v_mfma_f32_16x16x32_bf16 v[4:7], v[172:175], v[212:215], v[4:7]
	v_mfma_f32_16x16x32_bf16 v[0:3], v[180:183], v[212:215], v[0:3]
	s_setprio 0
	s_barrier
	s_add_i32 s46, s46, 2
	s_add_u32 s18, s18, 0x100
	s_addc_u32 s19, s19, 0
	s_add_u32 s44, s44, 0x100
	s_addc_u32 s45, s45, 0
	s_cmp_gt_u32 s46, 13
	s_cbranch_scc0 .LBB0_131
	s_and_b64 vcc, exec, s[6:7]
	s_cbranch_vccz .LBB0_134
	s_barrier
